# XCD-local seams (P4-P5, P5-P6, G4-G5, G5-G6) when run-time check shows every workgroup shares an XCC with workgroup blockIdx&7: no L2 writeback, no cross-XCD level
# speedup vs baseline: 1.0315x; 1.0096x over previous
; #define LAS __attribute__((address_space(3)))
; __device__ __forceinline__ unsigned xb_add(unsigned* p, unsigned v) { return __hip_atomic_fetch_add(p, v, __ATOMIC_RELAXED, __HIP_MEMORY_SCOPE_AGENT); }
; __device__ __forceinline__ unsigned xb_xcc_id() { return (unsigned)__builtin_amdgcn_s_getreg((3 << 11) | 20) & 0xFu; }
; __device__ __forceinline__ XcdBarrier xcd_barrier_post(unsigned* bar, volatile LAS unsigned* st) {
;     XcdBarrier b; b.bar = bar; b.x = xb_xcc_id(); b.st = st;
;     if (threadIdx.x == 0) (void)xb_add(&bar[XB_XCNT(b.x)], 1u);
;     return b;
; __global__ void __launch_bounds__(NTHR, 2) fwd_kernel(Args args) {
;     ...
;     volatile LAS unsigned* bst = (volatile LAS unsigned*)(lds + LDS_BYTES - 64);
;     if (tid < 2) bst[tid] = 0u;
;     __syncthreads();
;     const XcdBarrier bar = xcd_barrier_post((unsigned*)(ws + WS_BAR), bst);
_Z10fwd_kernel4Args:
	s_load_dwordx4 s[92:95], s[0:1], 0xb0
	s_load_dword s3, s[0:1], 0xc0
	v_and_b32_e32 v206, 0x3ff, v0
	s_add_u32 s68, s0, 0xc0
	v_readfirstlane_b32 s70, v206
	s_addc_u32 s69, s1, 0
	v_cmp_gt_u32_e32 vcc, 2, v206
	s_and_saveexec_b64 s[4:5], vcc
	v_lshl_add_u32 v1, v206, 2, 0
	v_add_u32_e32 v1, 0x25fc0, v1
	v_mov_b32_e32 v2, 0
	ds_write_b32 v1, v2
	s_or_b64 exec, exec, s[4:5]
	s_waitcnt lgkmcnt(0)
	s_barrier
	s_add_u32 s66, s92, 0x80000
	s_getreg_b32 s4, hwreg(HW_REG_XCC_ID, 0, 4)
	s_addc_u32 s67, s93, 0
	s_and_b32 s65, s4, 15
	v_cmp_eq_u32_e64 s[88:89], 0, v206
	s_mov_b32 s99, 0
	s_and_saveexec_b64 s[4:5], s[88:89]
	s_cbranch_execz .LBB0_5
	s_add_i32 s98, s65, 1
	v_mov_b32_e32 v3, s98
	s_lshl_b32 s98, s2, 2
	v_mov_b32_e32 v4, s98
	v_add_u32_e32 v4, 0x48000, v4
	global_store_dword v4, v3, s[92:93]
	s_mov_b64 s[6:7], exec
	v_mbcnt_lo_u32_b32 v1, s6, 0
	v_mbcnt_hi_u32_b32 v1, s7, v1
	v_cmp_eq_u32_e32 vcc, 0, v1
	s_and_b64 s[8:9], exec, vcc
	s_mov_b64 exec, s[8:9]
	s_cbranch_execz .LBB0_5
	s_lshl_b32 s8, s65, 8
	s_bcnt1_i32_b64 s6, s[6:7]
	v_mov_b32_e32 v1, s8
	v_mov_b32_e32 v2, s6
	global_atomic_add v1, v2, s[66:67] offset:1024

; #define PG8_STAGE(bufoff, gbase, voff) do { _Pragma("unroll") for (int _i = 0; _i < 2; ++_i) \
;         __builtin_amdgcn_global_load_lds((const unsigned*)((const char*)(gbase) + (voff)[_i]), (PG8_LAS unsigned*)(lds + (bufoff) + ldsw + _i * 8192), 16, 0, 0); } while (0)
; #define PG8_BAR __builtin_amdgcn_s_barrier()
;     __host__ __device__ bool next(int i, Unit& u) const {
;         const long L = (long)i * G + c; if (L >= nwg) return false;
;         int wgid = (int)L; { const int q = nwg / NXCD, r = nwg % NXCD, xcd = wgid % NXCD, off = wgid / NXCD; wgid = (xcd < r ? xcd * (q + 1) : r * (q + 1) + (xcd - r) * q) + off; }
;         const int nig = WGM * nN, gid = wgid / nig, fm = gid * WGM, gsz = (nM - fm) < WGM ? (nM - fm) : WGM;
;         u.pm = fm + ((wgid % nig) % gsz); u.pn = (wgid % nig) / gsz; return true;
; template <class Epi, class Sched, bool ALIGN_EPI = false, bool SP2 = false>
; __device__ __forceinline__ void gemm_phase(PG8_LAS unsigned char* lds, const Gemm g, const Sched& S, const Epi& E) {
;     ...
;     for (int i = 0; i < 2; ++i) { int R, C; stage_rc(tid * 16 + i * 8192, R, C); const int Rb = Epi::PERM ? ((R & ~31) + perm32(R & 31)) : R;
;         voffA[i] = (unsigned)(R * K + C) * 2u; voffB[i] = (unsigned)(Rb * K + C) * 2u; }
;     const size_t kstep = (size_t)(BK * 2);
;     const size_t hstep = (size_t)HALF * K * 2;
;     const size_t tstep = 2 * hstep;
;     const unsigned ldsw = (unsigned)wid * 1024u;
;     const int aoff = lds_byte(wr * 64 + fr, fq * 8), boff = lds_byte(wc * 32 + fr, fq * 8);
;     ...
;     Unit cur, nxt; int ui = 0;
;     if (!S.next(0, cur)) return;
;     f32x4 acc[2][2][4][2];
; #pragma unroll
;     for (int a = 0; a < 2; ++a)
; #pragma unroll
;         for (int b = 0; b < 2; ++b)
; #pragma unroll
;             for (int m = 0; m < 4; ++m)
; #pragma unroll
;                 for (int n = 0; n < 2; ++n) acc[a][b][m][n] = (f32x4){0.f, 0.f, 0.f, 0.f};
;     bf16x8 At[4][2], B0[2][2], B1[2][2];
;     const char* cA = (const char*)g.A + (size_t)cur.pm * tstep; const char* cB = (const char*)g.Bt + (size_t)cur.pn * tstep;
;     S.a_ready(cur);
;     if constexpr (SP2) {
;         PG8_STAGE(PG8_SB(0, 0), cB, voffB); PG8_STAGE(PG8_SB(0, 1), cB + hstep, voffB); PG8_STAGE(PG8_SA(0, 0), cA, voffA); PG8_STAGE(PG8_SA(0, 1), cA + hstep, voffA);
;         if (wr == 1) PG8_BAR;
.LBB0_130:
	s_and_saveexec_b64 s[100:101], s[88:89]
	s_cbranch_execz .Lplc_done
	s_and_b32 s98, s2, 7
	s_lshl_b32 s98, s98, 2
	v_mov_b32_e32 v0, s98
	v_add_u32_e32 v0, 0x48000, v0
	global_load_dword v1, v0, s[92:93] sc1
	s_add_i32 s98, s65, 1
	s_waitcnt vmcnt(0)
	v_cmp_ne_u32_e32 vcc, s98, v1
	s_cbranch_vccz .Lplc_done
	v_mov_b32_e32 v0, 0x48400
	v_mov_b32_e32 v1, 1
	global_atomic_add v0, v1, s[92:93]
.Lplc_done:
	s_or_b64 exec, exec, s[100:101]
	s_cmp_lt_i32 s94, 2
	s_cselect_b64 s[6:7], -1, 0
	s_add_u32 s56, s92, 0x2c00000
	s_addc_u32 s57, s93, 0
	s_add_u32 s54, s92, 0x4c00000
	s_addc_u32 s55, s93, 0
	s_and_b64 s[8:9], s[6:7], s[4:5]
	s_andn2_b64 vcc, exec, s[8:9]
	s_cbranch_vccnz .LBB0_237
	s_cmpk_gt_i32 s2, 0x57f
	v_readfirstlane_b32 s5, v206
	s_cbranch_scc1 .LBB0_147
	v_lshrrev_b32_e32 v0, 5, v206
	v_lshrrev_b32_e32 v2, 1, v206
	v_and_b32_e32 v0, 4, v0
	v_bfe_u32 v1, v206, 2, 2
	v_and_b32_e32 v11, 24, v2
	v_or3_b32 v0, v0, v1, v11
	v_lshlrev_b32_e32 v1, 4, v206
	v_add_u32_e32 v8, 0x2000, v1
	v_lshrrev_b32_e32 v2, 7, v8
	s_movk_i32 s4, 0xe0
	v_and_b32_e32 v4, 32, v206
	v_and_or_b32 v3, v2, s4, v0
	v_bitop3_b32 v9, v1, v4, 48 bitop3:0x6c
	v_and_b32_e32 v10, 64, v206
	v_bfe_u32 v12, v206, 2, 4
	s_movk_i32 s4, 0xf0
	v_or_b32_e32 v1, v9, v10
	v_and_or_b32 v2, v2, s4, v12
	s_add_u32 s30, s92, 0x1480000
	v_lshl_or_b32 v130, v2, 11, v1
	v_lshrrev_b32_e32 v2, 3, v206
	s_movk_i32 s4, 0x60
	s_addc_u32 s31, s93, 0
	v_and_or_b32 v0, v2, s4, v0
	s_movk_i32 s4, 0x70
	s_ashr_i32 s34, s2, 31
	v_lshl_or_b32 v132, v0, 11, v1
	v_and_or_b32 v0, v2, s4, v12
	s_lshr_b32 s4, s34, 29
	s_add_i32 s4, s2, s4
	s_lshr_b32 s12, s5, 6
	s_ashr_i32 s6, s4, 3
	s_and_b32 s4, s4, -8
	s_lshr_b32 s14, s5, 8
	s_lshl_b32 s33, s12, 10
	s_sub_i32 s4, s2, s4
	s_cmp_lt_i32 s4, 0
	s_movk_i32 s35, 0xb1
	s_cselect_b32 s7, s35, 0xb0
	s_mul_i32 s4, s4, s7
	s_add_i32 s4, s4, s6
	s_mul_hi_i32 s6, s4, 0x2e8ba2e9
	s_lshr_b32 s7, s6, 31
	s_ashr_i32 s6, s6, 5
	s_add_i32 s6, s6, s7
	s_lshl_b32 s7, s6, 3
	s_mulk_i32 s6, 0xb0
	s_sub_i32 s6, s4, s6
	s_bfe_u32 s4, s6, 0x3001c
	s_add_i32 s10, s6, s4
	s_sext_i32_i16 s4, s10
	s_and_b32 s10, s10, 0xfff8
	s_sub_i32 s6, s6, s10
	s_sext_i32_i16 s6, s6
	s_lshr_b32 s4, s4, 3
	s_add_i32 s6, s7, s6
	s_ashr_i32 s7, s6, 31
	s_bfe_i64 s[16:17], s[4:5], 0x100000
	s_lshl_b64 s[10:11], s[6:7], 19
	s_lshl_b64 s[16:17], s[16:17], 19
	s_add_u32 s26, s30, s16
	s_addc_u32 s27, s31, s17
	s_add_i32 s36, s33, 0
	s_add_i32 m0, s36, 0x10000
	v_lshl_or_b32 v128, v3, 11, v1
	global_load_lds_dwordx4 v132, s[26:27]
	s_add_i32 m0, s36, 0x12000
	s_add_u32 s16, s26, 0x40000
	global_load_lds_dwordx4 v128, s[26:27]
	s_addc_u32 s17, s27, 0
	s_add_i32 m0, s36, 0x14000
	v_lshl_or_b32 v134, v0, 11, v1
	global_load_lds_dwordx4 v132, s[16:17]
	s_add_i32 m0, s36, 0x16000
	s_add_u32 s24, s56, s10
	s_addc_u32 s25, s57, s11
	s_add_i32 s37, s36, 0x2000
	global_load_lds_dwordx4 v128, s[16:17]
	s_mov_b32 m0, s36
	s_add_u32 s10, s24, 0x40000
	global_load_lds_dwordx4 v134, s[24:25]
	s_mov_b32 m0, s37
	s_addc_u32 s11, s25, 0
	s_add_i32 s38, s36, 0x4000
	global_load_lds_dwordx4 v130, s[24:25]
	s_mov_b32 m0, s38
	s_add_i32 s39, s36, 0x6000
	global_load_lds_dwordx4 v134, s[10:11]
	s_mov_b32 m0, s39
	v_mov_b32_e32 v133, 0
	global_load_lds_dwordx4 v130, s[10:11]
	v_mov_b32_e32 v129, v133
	v_mov_b32_e32 v135, v133
	v_mov_b32_e32 v131, v133
	s_cmp_eq_u32 s14, 1
	s_mov_b32 s40, 0
	v_lshl_add_u64 v[6:7], s[26:27], 0, v[132:133]
	v_lshl_add_u64 v[4:5], s[26:27], 0, v[128:129]
	v_lshl_add_u64 v[0:1], s[24:25], 0, v[134:135]
	s_cselect_b64 s[10:11], -1, 0
	s_cmp_lg_u32 s14, 1
	v_lshl_add_u64 v[2:3], s[24:25], 0, v[130:131]
	s_cbranch_scc1 .LBB0_134
	s_barrier

;     __host__ __device__ bool next(int i, Unit& u) const {
;         const long L = (long)i * G + c; if (L >= nwg) return false;
;         int wgid = (int)L; { const int q = nwg / NXCD, r = nwg % NXCD, xcd = wgid % NXCD, off = wgid / NXCD; wgid = (xcd < r ? xcd * (q + 1) : r * (q + 1) + (xcd - r) * q) + off; }
;         const int nig = WGM * nN, gid = wgid / nig, fm = gid * WGM, gsz = (nM - fm) < WGM ? (nM - fm) : WGM;
;         u.pm = fm + ((wgid % nig) % gsz); u.pn = (wgid % nig) / gsz; return true;
; __global__ void __launch_bounds__(NTHR, 2) fwd_kernel(Args args) {
;     ...
;     if (IN(2)) { pg8::Gemm g{HB, (const bf16*)(ws + WS_WD1), M, D, FF}; pg8::StaticOrder S; S.init(M, D, G, (int)blockIdx.x);
;         EpiResid E{args.in[0], args.out, XB, ss + M, 0.5f}; pg8::gemm_phase<EpiResid, pg8::StaticOrder, true, true>(lds, g, S, E); }
.LBB0_291:
	s_and_saveexec_b64 s[100:101], s[88:89]
	s_cbranch_execz .Lmode_done
	v_mov_b32_e32 v0, 0x48400
	global_load_dword v1, v0, s[92:93] sc1
	s_waitcnt vmcnt(0)
	v_readfirstlane_b32 s98, v1
	s_nop 3
	s_cmp_eq_u32 s98, 0
	s_cselect_b32 s99, 1, 0
.Lmode_done:
	s_or_b64 exec, exec, s[100:101]
	s_cmp_lt_i32 s94, 3
	s_cselect_b64 s[6:7], -1, 0
	s_and_b64 s[10:11], s[6:7], s[4:5]
	s_andn2_b64 vcc, exec, s[10:11]
	s_cbranch_vccnz .LBB0_338
	s_load_dwordx2 s[12:13], s[0:1], 0x0
	s_load_dwordx2 s[14:15], s[0:1], 0xa8
	s_cmpk_lt_i32 s2, 0x100
	s_cselect_b64 s[4:5], -1, 0
	s_cmpk_gt_i32 s2, 0xff
	v_readfirstlane_b32 s8, v206
	s_cbranch_scc1 .LBB0_298
	s_ashr_i32 s6, s2, 31
	s_lshr_b32 s6, s6, 29
	s_add_i32 s17, s2, s6
	s_and_b32 s6, s17, -8
	s_sub_i32 s9, s2, s6
	s_cmp_gt_i32 s9, -1
	s_cbranch_scc0 .LBB0_295
	s_lshl_b32 s16, s9, 5
	s_ashr_i32 s6, s17, 3
	s_cbranch_execz .LBB0_296
	s_branch .LBB0_297

; __device__ __forceinline__ unsigned xb_ld(unsigned* p)              { return __hip_atomic_load(p, __ATOMIC_RELAXED, __HIP_MEMORY_SCOPE_AGENT); }
; __device__ __forceinline__ unsigned xb_add(unsigned* p, unsigned v) { return __hip_atomic_fetch_add(p, v, __ATOMIC_RELAXED, __HIP_MEMORY_SCOPE_AGENT); }
; #define XB_SPIN(cond, bar) do { unsigned _sp = 0; while (cond) { __builtin_amdgcn_s_sleep(1); \
;     if ((++_sp & 255u) == 0u) { if (xb_ld(&(bar)[XB_TMO])) break; if (_sp > XB_SPIN_CAP) { atomicAdd(&(bar)[XB_TMO], 1u); break; } } } } while (0)
; __device__ __forceinline__ void xcd_barrier(const XcdBarrier& b) {
;     ...
;         const unsigned old = xb_add(&bar[XB_XSUB(b.x)], 1u);
;         const unsigned gen = old / nloc;
;         if (old + 1u == (gen + 1u) * nloc) {
;             __builtin_amdgcn_fence(__ATOMIC_RELEASE, "agent");
;             asm volatile("s_waitcnt vmcnt(0)" ::: "memory");
;             const unsigned og = xb_add(&bar[XB_TOP], 1u);
;             const unsigned tg = og / nx;
;             if (og + 1u == (tg + 1u) * nx) xb_add(&bar[XB_TOPGEN], 1u);
;             else XB_SPIN(xb_ld(&bar[XB_TOPGEN]) == tg, bar);
;             __builtin_amdgcn_fence(__ATOMIC_ACQUIRE, "agent");
;             xb_add(&bar[XB_XGEN(b.x)], 1u);
.LBB0_926:
	s_andn2_saveexec_b64 s[10:11], s[10:11]
	s_cbranch_execz .LBB0_946
	s_mov_b64 s[10:11], exec
	s_cmp_eq_u32 s99, 1
	s_cbranch_scc1 .Lloc_4
	buffer_wbl2 sc1
	s_waitcnt lgkmcnt(0)
	s_waitcnt vmcnt(0)
	buffer_inv sc1
	v_mbcnt_lo_u32_b32 v1, s10, 0
	v_mbcnt_hi_u32_b32 v1, s11, v1
	v_cmp_eq_u32_e32 vcc, 0, v1
	s_and_saveexec_b64 s[12:13], vcc
	s_cbranch_execz .LBB0_929
	s_bcnt1_i32_b64 s10, s[10:11]
	v_mov_b32_e32 v2, 0x83000
	v_mov_b32_e32 v3, s10
	global_atomic_add v2, v2, v3, s[92:93] offset:1024 sc0

; __device__ __forceinline__ unsigned xb_add(unsigned* p, unsigned v) { return __hip_atomic_fetch_add(p, v, __ATOMIC_RELAXED, __HIP_MEMORY_SCOPE_AGENT); }
; __device__ __forceinline__ void xcd_barrier(const XcdBarrier& b) {
;     ...
;             __builtin_amdgcn_fence(__ATOMIC_ACQUIRE, "agent");
;             xb_add(&bar[XB_XGEN(b.x)], 1u);
;             asm volatile("s_waitcnt vmcnt(0)" ::: "memory");
.LBB0_945:
	s_or_b64 exec, exec, s[12:13]
	s_nop 0
	s_branch .LBB0_946
.Lloc_4:
	buffer_inv sc1
	v_mov_b32_e32 v0, 0x2000
	v_mov_b32_e32 v1, 1
	global_atomic_add v0, v1, s[8:9] offset:1024
	s_waitcnt vmcnt(0)

; __global__ void __launch_bounds__(NTHR, 2) fwd_kernel(Args args) {
	.amdhsa_kernel _Z10fwd_kernel4Args
		.amdhsa_group_segment_fixed_size 0
		.amdhsa_private_segment_fixed_size 0
		.amdhsa_kernarg_size 448
		.amdhsa_user_sgpr_count 2
		.amdhsa_user_sgpr_dispatch_ptr 0
		.amdhsa_user_sgpr_queue_ptr 0
		.amdhsa_user_sgpr_kernarg_segment_ptr 1
		.amdhsa_user_sgpr_dispatch_id 0
		.amdhsa_user_sgpr_kernarg_preload_length 0
		.amdhsa_user_sgpr_kernarg_preload_offset 0
		.amdhsa_user_sgpr_private_segment_size 0
		.amdhsa_uses_dynamic_stack 0
		.amdhsa_enable_private_segment 0
		.amdhsa_system_sgpr_workgroup_id_x 1
		.amdhsa_system_sgpr_workgroup_id_y 0
		.amdhsa_system_sgpr_workgroup_id_z 0
		.amdhsa_system_sgpr_workgroup_info 0
		.amdhsa_system_vgpr_workitem_id 2
		.amdhsa_next_free_vgpr 256
		.amdhsa_next_free_sgpr 102
		.amdhsa_accum_offset 256
		.amdhsa_reserve_vcc 1
		.amdhsa_float_round_mode_32 0
		.amdhsa_float_round_mode_16_64 0
		.amdhsa_float_denorm_mode_32 3
		.amdhsa_float_denorm_mode_16_64 3
		.amdhsa_dx10_clamp 1
		.amdhsa_ieee_mode 1
		.amdhsa_fp16_overflow 0
		.amdhsa_tg_split 0
		.amdhsa_exception_fp_ieee_invalid_op 0
		.amdhsa_exception_fp_denorm_src 0
		.amdhsa_exception_fp_ieee_div_zero 0
		.amdhsa_exception_fp_ieee_overflow 0
		.amdhsa_exception_fp_ieee_underflow 0
		.amdhsa_exception_fp_ieee_inexact 0
		.amdhsa_exception_int_div_zero 0
	.end_amdhsa_kernel

; __global__ void __launch_bounds__(NTHR, 2) fwd_kernel(Args args) {
amdhsa.kernels:
  - .agpr_count:     0
    .args:
      - .offset:         0
        .size:           192
        .value_kind:     by_value
      - .offset:         192
        .size:           4
        .value_kind:     hidden_block_count_x
      - .offset:         196
        .size:           4
        .value_kind:     hidden_block_count_y
      - .offset:         200
        .size:           4
        .value_kind:     hidden_block_count_z
      - .offset:         204
        .size:           2
        .value_kind:     hidden_group_size_x
      - .offset:         206
        .size:           2
        .value_kind:     hidden_group_size_y
      - .offset:         208
        .size:           2
        .value_kind:     hidden_group_size_z
      - .offset:         210
        .size:           2
        .value_kind:     hidden_remainder_x
      - .offset:         212
        .size:           2
        .value_kind:     hidden_remainder_y
      - .offset:         214
        .size:           2
        .value_kind:     hidden_remainder_z
      - .offset:         232
        .size:           8
        .value_kind:     hidden_global_offset_x
      - .offset:         240
        .size:           8
        .value_kind:     hidden_global_offset_y
      - .offset:         248
        .size:           8
        .value_kind:     hidden_global_offset_z
      - .offset:         256
        .size:           2
        .value_kind:     hidden_grid_dims
      - .offset:         280
        .size:           8
        .value_kind:     hidden_multigrid_sync_arg
      - .offset:         312
        .size:           4
        .value_kind:     hidden_dynamic_lds_size
    .group_segment_fixed_size: 0
    .kernarg_segment_align: 8
    .kernarg_segment_size: 448
    .language:       OpenCL C
    .language_version:
      - 2
      - 0
    .max_flat_workgroup_size: 512
    .name:           _Z10fwd_kernel4Args
    .private_segment_fixed_size: 0
    .sgpr_count:     108
    .sgpr_spill_count: 56
    .symbol:         _Z10fwd_kernel4Args.kd
    .uniform_work_group_size: 1
    .uses_dynamic_stack: false
    .vgpr_count:     256
    .vgpr_spill_count: 0
    .wavefront_size: 64
